# hand-written software-pipelined 8-tile batched weight transposes in prologue and mixer queues
# speedup vs baseline: 1.2247x; 1.0049x over previous
.LBB0_31:
	s_or_b64 exec, exec, s[20:21]
	s_waitcnt lgkmcnt(0)
	s_barrier
	ds_read_b32 v0, v13 offset:53264
	s_movk_i32 s0, 0x287
	s_mov_b64 s[20:21], -1
	s_waitcnt lgkmcnt(0)
	v_cmp_lt_i32_e32 vcc, s0, v0
	v_readfirstlane_b32 s34, v0
	s_cbranch_vccnz .LBB0_26
	s_cmpk_gt_i32 s34, 0x11f
	s_cbranch_scc0 .LBB0_54
	s_sub_u32 s34, s34, 288
	s_lshl_b32 s34, s34, 3
	s_add_u32 s34, s34, 288
	s_add_i32 s35, s34, 0xfffffee0
	s_cmpk_lt_u32 s35, 0x580
	s_cbranch_scc1 .LBB0_38
	s_cmpk_gt_u32 s35, 0x83f
	s_cbranch_scc0 .LBB0_36
	s_add_i32 s35, s34, 0x17a0
	s_mov_b64 s[20:21], 0

.LBB0_45:
	s_and_b32 s26, 0xffff, s37
	v_cvt_f32_u32_e32 v0, s26
	s_and_b32 s26, 0xffff, s36
	v_cvt_f32_u32_e32 v1, s26
	v_mov_b32_e32 v8, v128
	v_rcp_iflag_f32_e32 v2, v0
	v_mov_b32_e32 v4, 0
	v_ashrrev_i32_e32 v9, 4, v8
	v_mul_f32_e32 v2, v1, v2
	v_trunc_f32_e32 v2, v2
	v_cvt_u32_f32_e32 v3, v2
	v_fma_f32 v1, -v2, v0, v1
	v_cmp_ge_f32_e64 s[26:27], |v1|, v0
	s_cmp_lg_u64 s[26:27], 0
	v_readfirstlane_b32 s26, v3
	s_addc_u32 s26, s26, 0
	s_and_b32 s27, s26, 0xffff
	s_mul_i32 s35, s26, s37
	s_lshl_b32 s26, s27, 6
	s_sub_i32 s27, s36, s35
	s_lshl_b32 s27, s27, 6
	v_lshlrev_b32_e32 v0, 2, v8
	s_and_b32 s27, s27, 0xffc0
	v_and_b32_e32 v1, 60, v0
	v_or_b32_e32 v0, s27, v1
	v_lshlrev_b32_e32 v12, 2, v0
	v_cmp_gt_u32_e32 vcc, s0, v0
	v_lshl_add_u64 v[6:7], s[24:25], 0, v[12:13]
	v_lshrrev_b32_e32 v36, 4, v128
	v_and_b32_e32 v37, 15, v128
	v_lshlrev_b32_e32 v37, 2, v37
	s_movk_i32 s50, 0x104
	v_mul_lo_u32 v41, v36, s50
	v_lshl_add_u32 v20, v37, 2, v41
	v_add_u32_e32 v21, 0x1040, v20
	v_add_u32_e32 v22, 0x2080, v20
	v_add_u32_e32 v23, 0x30c0, v20
	v_add_u32_e32 v24, 0x4200, v20
	v_add_u32_e32 v25, 0x4200, v21
	v_add_u32_e32 v26, 0x4200, v22
	v_add_u32_e32 v27, 0x4200, v23
	v_and_b32_e32 v41, 3, v128
	v_lshlrev_b32_e32 v41, 4, v41
	v_mul_lo_u32 v28, v41, s50
	v_and_b32_e32 v42, -4, v128
	v_add_u32_e32 v28, v28, v42
	v_add_u32_e32 v29, 0x400, v28
	v_add_u32_e32 v30, 0x800, v28
	v_add_u32_e32 v31, 0xc00, v28
	v_add_u32_e32 v32, 0x4200, v28
	v_add_u32_e32 v33, 0x4200, v29
	v_add_u32_e32 v34, 0x4200, v30
	v_add_u32_e32 v35, 0x4200, v31
	v_add_u32_e32 v38, s26, v36
	v_mul_lo_u32 v38, v38, s0
	v_lshlrev_b32_e32 v38, 2, v38
	s_lshl_b32 s51, s0, 6
	s_sub_u32 s52, s0, 4
	v_lshrrev_b32_e32 v39, 2, v128
	v_add_u32_e32 v39, s27, v39
	v_mul_lo_u32 v39, v39, s22
	v_add_u32_e32 v39, s26, v39
	v_add_u32_e32 v39, v41, v39
	v_lshlrev_b32_e32 v39, 1, v39
	s_lshl_b32 s53, s22, 7
	v_add_u32_e32 v40, s27, v37
	v_min_u32_e32 v40, s52, v40
	v_lshl_add_u32 v224, v40, 2, v38
	v_add_u32_e32 v225, s51, v224
	v_add_u32_e32 v226, s51, v225
	v_add_u32_e32 v227, s51, v226
	global_load_dwordx4 v[168:171], v224, s[24:25] nt
	global_load_dwordx4 v[172:175], v225, s[24:25] nt
	global_load_dwordx4 v[176:179], v226, s[24:25] nt
	global_load_dwordx4 v[180:183], v227, s[24:25] nt
	v_add_u32_e32 v40, s27, v37
	v_add_u32_e32 v40, 64, v40
	v_min_u32_e32 v40, s52, v40
	v_lshl_add_u32 v224, v40, 2, v38
	v_add_u32_e32 v225, s51, v224
	v_add_u32_e32 v226, s51, v225
	v_add_u32_e32 v227, s51, v226
	global_load_dwordx4 v[184:187], v224, s[24:25] nt
	global_load_dwordx4 v[188:191], v225, s[24:25] nt
	global_load_dwordx4 v[192:195], v226, s[24:25] nt
	global_load_dwordx4 v[196:199], v227, s[24:25] nt
	s_waitcnt vmcnt(4)
	v_add_u32_e32 v40, s27, v37
	v_cmp_gt_u32_e32 vcc, s0, v40
	s_nop 1
	v_cndmask_b32_e32 v168, 0, v168, vcc
	v_cndmask_b32_e32 v169, 0, v169, vcc
	v_cndmask_b32_e32 v170, 0, v170, vcc
	v_cndmask_b32_e32 v171, 0, v171, vcc
	v_cndmask_b32_e32 v172, 0, v172, vcc
	v_cndmask_b32_e32 v173, 0, v173, vcc
	v_cndmask_b32_e32 v174, 0, v174, vcc
	v_cndmask_b32_e32 v175, 0, v175, vcc
	v_cndmask_b32_e32 v176, 0, v176, vcc
	v_cndmask_b32_e32 v177, 0, v177, vcc
	v_cndmask_b32_e32 v178, 0, v178, vcc
	v_cndmask_b32_e32 v179, 0, v179, vcc
	v_cndmask_b32_e32 v180, 0, v180, vcc
	v_cndmask_b32_e32 v181, 0, v181, vcc
	v_cndmask_b32_e32 v182, 0, v182, vcc
	v_cndmask_b32_e32 v183, 0, v183, vcc
	ds_write2_b32 v20, v168, v169 offset1:1
	ds_write2_b32 v20, v170, v171 offset0:2 offset1:3
	ds_write2_b32 v21, v172, v173 offset1:1
	ds_write2_b32 v21, v174, v175 offset0:2 offset1:3
	ds_write2_b32 v22, v176, v177 offset1:1
	ds_write2_b32 v22, v178, v179 offset0:2 offset1:3
	ds_write2_b32 v23, v180, v181 offset1:1
	ds_write2_b32 v23, v182, v183 offset0:2 offset1:3
	s_waitcnt lgkmcnt(0)
	s_barrier
	v_add_u32_e32 v40, s27, v37
	v_add_u32_e32 v40, 128, v40
	v_min_u32_e32 v40, s52, v40
	v_lshl_add_u32 v224, v40, 2, v38
	v_add_u32_e32 v225, s51, v224
	v_add_u32_e32 v226, s51, v225
	v_add_u32_e32 v227, s51, v226
	global_load_dwordx4 v[168:171], v224, s[24:25] nt
	global_load_dwordx4 v[172:175], v225, s[24:25] nt
	global_load_dwordx4 v[176:179], v226, s[24:25] nt
	global_load_dwordx4 v[180:183], v227, s[24:25] nt
	ds_read2_b32 v[200:201], v28 offset0:0 offset1:65
	ds_read2_b32 v[202:203], v28 offset0:130 offset1:195
	ds_read2_b32 v[204:205], v29 offset0:4 offset1:69
	ds_read2_b32 v[206:207], v29 offset0:134 offset1:199
	ds_read2_b32 v[208:209], v30 offset0:8 offset1:73
	ds_read2_b32 v[210:211], v30 offset0:138 offset1:203
	ds_read2_b32 v[212:213], v31 offset0:12 offset1:77
	ds_read2_b32 v[214:215], v31 offset0:142 offset1:207
	s_waitcnt lgkmcnt(0)
	v_cvt_pk_bf16_f32 v216, v200, v201
	v_cvt_pk_bf16_f32 v217, v202, v203
	v_cvt_pk_bf16_f32 v218, v204, v205
	v_cvt_pk_bf16_f32 v219, v206, v207
	v_cvt_pk_bf16_f32 v220, v208, v209
	v_cvt_pk_bf16_f32 v221, v210, v211
	v_cvt_pk_bf16_f32 v222, v212, v213
	v_cvt_pk_bf16_f32 v223, v214, v215
	global_store_dwordx4 v39, v[216:219], s[20:21]
	global_store_dwordx4 v39, v[220:223], s[20:21] offset:16
	v_add_u32_e32 v39, s53, v39
	s_waitcnt vmcnt(6)
	v_add_u32_e32 v40, s27, v37
	v_add_u32_e32 v40, 64, v40
	v_cmp_gt_u32_e32 vcc, s0, v40
	s_nop 1
	v_cndmask_b32_e32 v184, 0, v184, vcc
	v_cndmask_b32_e32 v185, 0, v185, vcc
	v_cndmask_b32_e32 v186, 0, v186, vcc
	v_cndmask_b32_e32 v187, 0, v187, vcc
	v_cndmask_b32_e32 v188, 0, v188, vcc
	v_cndmask_b32_e32 v189, 0, v189, vcc
	v_cndmask_b32_e32 v190, 0, v190, vcc
	v_cndmask_b32_e32 v191, 0, v191, vcc
	v_cndmask_b32_e32 v192, 0, v192, vcc
	v_cndmask_b32_e32 v193, 0, v193, vcc
	v_cndmask_b32_e32 v194, 0, v194, vcc
	v_cndmask_b32_e32 v195, 0, v195, vcc
	v_cndmask_b32_e32 v196, 0, v196, vcc
	v_cndmask_b32_e32 v197, 0, v197, vcc
	v_cndmask_b32_e32 v198, 0, v198, vcc
	v_cndmask_b32_e32 v199, 0, v199, vcc
	ds_write2_b32 v24, v184, v185 offset1:1
	ds_write2_b32 v24, v186, v187 offset0:2 offset1:3
	ds_write2_b32 v25, v188, v189 offset1:1
	ds_write2_b32 v25, v190, v191 offset0:2 offset1:3
	ds_write2_b32 v26, v192, v193 offset1:1
	ds_write2_b32 v26, v194, v195 offset0:2 offset1:3
	ds_write2_b32 v27, v196, v197 offset1:1
	ds_write2_b32 v27, v198, v199 offset0:2 offset1:3
	s_waitcnt lgkmcnt(0)
	s_barrier
	v_add_u32_e32 v40, s27, v37
	v_add_u32_e32 v40, 192, v40
	v_min_u32_e32 v40, s52, v40
	v_lshl_add_u32 v224, v40, 2, v38
	v_add_u32_e32 v225, s51, v224
	v_add_u32_e32 v226, s51, v225
	v_add_u32_e32 v227, s51, v226
	global_load_dwordx4 v[184:187], v224, s[24:25] nt
	global_load_dwordx4 v[188:191], v225, s[24:25] nt
	global_load_dwordx4 v[192:195], v226, s[24:25] nt
	global_load_dwordx4 v[196:199], v227, s[24:25] nt
	ds_read2_b32 v[200:201], v32 offset0:0 offset1:65
	ds_read2_b32 v[202:203], v32 offset0:130 offset1:195
	ds_read2_b32 v[204:205], v33 offset0:4 offset1:69
	ds_read2_b32 v[206:207], v33 offset0:134 offset1:199
	ds_read2_b32 v[208:209], v34 offset0:8 offset1:73
	ds_read2_b32 v[210:211], v34 offset0:138 offset1:203
	ds_read2_b32 v[212:213], v35 offset0:12 offset1:77
	ds_read2_b32 v[214:215], v35 offset0:142 offset1:207
	s_waitcnt lgkmcnt(0)
	v_cvt_pk_bf16_f32 v216, v200, v201
	v_cvt_pk_bf16_f32 v217, v202, v203
	v_cvt_pk_bf16_f32 v218, v204, v205
	v_cvt_pk_bf16_f32 v219, v206, v207
	v_cvt_pk_bf16_f32 v220, v208, v209
	v_cvt_pk_bf16_f32 v221, v210, v211
	v_cvt_pk_bf16_f32 v222, v212, v213
	v_cvt_pk_bf16_f32 v223, v214, v215
	global_store_dwordx4 v39, v[216:219], s[20:21]
	global_store_dwordx4 v39, v[220:223], s[20:21] offset:16
	v_add_u32_e32 v39, s53, v39
	s_waitcnt vmcnt(8)
	v_add_u32_e32 v40, s27, v37
	v_add_u32_e32 v40, 128, v40
	v_cmp_gt_u32_e32 vcc, s0, v40
	s_nop 1
	v_cndmask_b32_e32 v168, 0, v168, vcc
	v_cndmask_b32_e32 v169, 0, v169, vcc
	v_cndmask_b32_e32 v170, 0, v170, vcc
	v_cndmask_b32_e32 v171, 0, v171, vcc
	v_cndmask_b32_e32 v172, 0, v172, vcc
	v_cndmask_b32_e32 v173, 0, v173, vcc
	v_cndmask_b32_e32 v174, 0, v174, vcc
	v_cndmask_b32_e32 v175, 0, v175, vcc
	v_cndmask_b32_e32 v176, 0, v176, vcc
	v_cndmask_b32_e32 v177, 0, v177, vcc
	v_cndmask_b32_e32 v178, 0, v178, vcc
	v_cndmask_b32_e32 v179, 0, v179, vcc
	v_cndmask_b32_e32 v180, 0, v180, vcc
	v_cndmask_b32_e32 v181, 0, v181, vcc
	v_cndmask_b32_e32 v182, 0, v182, vcc
	v_cndmask_b32_e32 v183, 0, v183, vcc
	ds_write2_b32 v20, v168, v169 offset1:1
	ds_write2_b32 v20, v170, v171 offset0:2 offset1:3
	ds_write2_b32 v21, v172, v173 offset1:1
	ds_write2_b32 v21, v174, v175 offset0:2 offset1:3
	ds_write2_b32 v22, v176, v177 offset1:1
	ds_write2_b32 v22, v178, v179 offset0:2 offset1:3
	ds_write2_b32 v23, v180, v181 offset1:1
	ds_write2_b32 v23, v182, v183 offset0:2 offset1:3
	s_waitcnt lgkmcnt(0)
	s_barrier
	v_add_u32_e32 v40, s27, v37
	v_add_u32_e32 v40, 256, v40
	v_min_u32_e32 v40, s52, v40
	v_lshl_add_u32 v224, v40, 2, v38
	v_add_u32_e32 v225, s51, v224
	v_add_u32_e32 v226, s51, v225
	v_add_u32_e32 v227, s51, v226
	global_load_dwordx4 v[168:171], v224, s[24:25] nt
	global_load_dwordx4 v[172:175], v225, s[24:25] nt
	global_load_dwordx4 v[176:179], v226, s[24:25] nt
	global_load_dwordx4 v[180:183], v227, s[24:25] nt
	ds_read2_b32 v[200:201], v28 offset0:0 offset1:65
	ds_read2_b32 v[202:203], v28 offset0:130 offset1:195
	ds_read2_b32 v[204:205], v29 offset0:4 offset1:69
	ds_read2_b32 v[206:207], v29 offset0:134 offset1:199
	ds_read2_b32 v[208:209], v30 offset0:8 offset1:73
	ds_read2_b32 v[210:211], v30 offset0:138 offset1:203
	ds_read2_b32 v[212:213], v31 offset0:12 offset1:77
	ds_read2_b32 v[214:215], v31 offset0:142 offset1:207
	s_waitcnt lgkmcnt(0)
	v_cvt_pk_bf16_f32 v216, v200, v201
	v_cvt_pk_bf16_f32 v217, v202, v203
	v_cvt_pk_bf16_f32 v218, v204, v205
	v_cvt_pk_bf16_f32 v219, v206, v207
	v_cvt_pk_bf16_f32 v220, v208, v209
	v_cvt_pk_bf16_f32 v221, v210, v211
	v_cvt_pk_bf16_f32 v222, v212, v213
	v_cvt_pk_bf16_f32 v223, v214, v215
	global_store_dwordx4 v39, v[216:219], s[20:21]
	global_store_dwordx4 v39, v[220:223], s[20:21] offset:16
	v_add_u32_e32 v39, s53, v39
	s_waitcnt vmcnt(8)
	v_add_u32_e32 v40, s27, v37
	v_add_u32_e32 v40, 192, v40
	v_cmp_gt_u32_e32 vcc, s0, v40
	s_nop 1
	v_cndmask_b32_e32 v184, 0, v184, vcc
	v_cndmask_b32_e32 v185, 0, v185, vcc
	v_cndmask_b32_e32 v186, 0, v186, vcc
	v_cndmask_b32_e32 v187, 0, v187, vcc
	v_cndmask_b32_e32 v188, 0, v188, vcc
	v_cndmask_b32_e32 v189, 0, v189, vcc
	v_cndmask_b32_e32 v190, 0, v190, vcc
	v_cndmask_b32_e32 v191, 0, v191, vcc
	v_cndmask_b32_e32 v192, 0, v192, vcc
	v_cndmask_b32_e32 v193, 0, v193, vcc
	v_cndmask_b32_e32 v194, 0, v194, vcc
	v_cndmask_b32_e32 v195, 0, v195, vcc
	v_cndmask_b32_e32 v196, 0, v196, vcc
	v_cndmask_b32_e32 v197, 0, v197, vcc
	v_cndmask_b32_e32 v198, 0, v198, vcc
	v_cndmask_b32_e32 v199, 0, v199, vcc
	ds_write2_b32 v24, v184, v185 offset1:1
	ds_write2_b32 v24, v186, v187 offset0:2 offset1:3
	ds_write2_b32 v25, v188, v189 offset1:1
	ds_write2_b32 v25, v190, v191 offset0:2 offset1:3
	ds_write2_b32 v26, v192, v193 offset1:1
	ds_write2_b32 v26, v194, v195 offset0:2 offset1:3
	ds_write2_b32 v27, v196, v197 offset1:1
	ds_write2_b32 v27, v198, v199 offset0:2 offset1:3
	s_waitcnt lgkmcnt(0)
	s_barrier
	v_add_u32_e32 v40, s27, v37
	v_add_u32_e32 v40, 320, v40
	v_min_u32_e32 v40, s52, v40
	v_lshl_add_u32 v224, v40, 2, v38
	v_add_u32_e32 v225, s51, v224
	v_add_u32_e32 v226, s51, v225
	v_add_u32_e32 v227, s51, v226
	global_load_dwordx4 v[184:187], v224, s[24:25] nt
	global_load_dwordx4 v[188:191], v225, s[24:25] nt
	global_load_dwordx4 v[192:195], v226, s[24:25] nt
	global_load_dwordx4 v[196:199], v227, s[24:25] nt
	ds_read2_b32 v[200:201], v32 offset0:0 offset1:65
	ds_read2_b32 v[202:203], v32 offset0:130 offset1:195
	ds_read2_b32 v[204:205], v33 offset0:4 offset1:69
	ds_read2_b32 v[206:207], v33 offset0:134 offset1:199
	ds_read2_b32 v[208:209], v34 offset0:8 offset1:73
	ds_read2_b32 v[210:211], v34 offset0:138 offset1:203
	ds_read2_b32 v[212:213], v35 offset0:12 offset1:77
	ds_read2_b32 v[214:215], v35 offset0:142 offset1:207
	s_waitcnt lgkmcnt(0)
	v_cvt_pk_bf16_f32 v216, v200, v201
	v_cvt_pk_bf16_f32 v217, v202, v203
	v_cvt_pk_bf16_f32 v218, v204, v205
	v_cvt_pk_bf16_f32 v219, v206, v207
	v_cvt_pk_bf16_f32 v220, v208, v209
	v_cvt_pk_bf16_f32 v221, v210, v211
	v_cvt_pk_bf16_f32 v222, v212, v213
	v_cvt_pk_bf16_f32 v223, v214, v215
	global_store_dwordx4 v39, v[216:219], s[20:21]
	global_store_dwordx4 v39, v[220:223], s[20:21] offset:16
	v_add_u32_e32 v39, s53, v39
	s_waitcnt vmcnt(8)
	v_add_u32_e32 v40, s27, v37
	v_add_u32_e32 v40, 256, v40
	v_cmp_gt_u32_e32 vcc, s0, v40
	s_nop 1
	v_cndmask_b32_e32 v168, 0, v168, vcc
	v_cndmask_b32_e32 v169, 0, v169, vcc
	v_cndmask_b32_e32 v170, 0, v170, vcc
	v_cndmask_b32_e32 v171, 0, v171, vcc
	v_cndmask_b32_e32 v172, 0, v172, vcc
	v_cndmask_b32_e32 v173, 0, v173, vcc
	v_cndmask_b32_e32 v174, 0, v174, vcc
	v_cndmask_b32_e32 v175, 0, v175, vcc
	v_cndmask_b32_e32 v176, 0, v176, vcc
	v_cndmask_b32_e32 v177, 0, v177, vcc
	v_cndmask_b32_e32 v178, 0, v178, vcc
	v_cndmask_b32_e32 v179, 0, v179, vcc
	v_cndmask_b32_e32 v180, 0, v180, vcc
	v_cndmask_b32_e32 v181, 0, v181, vcc
	v_cndmask_b32_e32 v182, 0, v182, vcc
	v_cndmask_b32_e32 v183, 0, v183, vcc
	ds_write2_b32 v20, v168, v169 offset1:1
	ds_write2_b32 v20, v170, v171 offset0:2 offset1:3
	ds_write2_b32 v21, v172, v173 offset1:1
	ds_write2_b32 v21, v174, v175 offset0:2 offset1:3
	ds_write2_b32 v22, v176, v177 offset1:1
	ds_write2_b32 v22, v178, v179 offset0:2 offset1:3
	ds_write2_b32 v23, v180, v181 offset1:1
	ds_write2_b32 v23, v182, v183 offset0:2 offset1:3
	s_waitcnt lgkmcnt(0)
	s_barrier
	v_add_u32_e32 v40, s27, v37
	v_add_u32_e32 v40, 384, v40
	v_min_u32_e32 v40, s52, v40
	v_lshl_add_u32 v224, v40, 2, v38
	v_add_u32_e32 v225, s51, v224
	v_add_u32_e32 v226, s51, v225
	v_add_u32_e32 v227, s51, v226
	global_load_dwordx4 v[168:171], v224, s[24:25] nt
	global_load_dwordx4 v[172:175], v225, s[24:25] nt
	global_load_dwordx4 v[176:179], v226, s[24:25] nt
	global_load_dwordx4 v[180:183], v227, s[24:25] nt
	ds_read2_b32 v[200:201], v28 offset0:0 offset1:65
	ds_read2_b32 v[202:203], v28 offset0:130 offset1:195
	ds_read2_b32 v[204:205], v29 offset0:4 offset1:69
	ds_read2_b32 v[206:207], v29 offset0:134 offset1:199
	ds_read2_b32 v[208:209], v30 offset0:8 offset1:73
	ds_read2_b32 v[210:211], v30 offset0:138 offset1:203
	ds_read2_b32 v[212:213], v31 offset0:12 offset1:77
	ds_read2_b32 v[214:215], v31 offset0:142 offset1:207
	s_waitcnt lgkmcnt(0)
	v_cvt_pk_bf16_f32 v216, v200, v201
	v_cvt_pk_bf16_f32 v217, v202, v203
	v_cvt_pk_bf16_f32 v218, v204, v205
	v_cvt_pk_bf16_f32 v219, v206, v207
	v_cvt_pk_bf16_f32 v220, v208, v209
	v_cvt_pk_bf16_f32 v221, v210, v211
	v_cvt_pk_bf16_f32 v222, v212, v213
	v_cvt_pk_bf16_f32 v223, v214, v215
	global_store_dwordx4 v39, v[216:219], s[20:21]
	global_store_dwordx4 v39, v[220:223], s[20:21] offset:16
	v_add_u32_e32 v39, s53, v39
	s_waitcnt vmcnt(8)
	v_add_u32_e32 v40, s27, v37
	v_add_u32_e32 v40, 320, v40
	v_cmp_gt_u32_e32 vcc, s0, v40
	s_nop 1
	v_cndmask_b32_e32 v184, 0, v184, vcc
	v_cndmask_b32_e32 v185, 0, v185, vcc
	v_cndmask_b32_e32 v186, 0, v186, vcc
	v_cndmask_b32_e32 v187, 0, v187, vcc
	v_cndmask_b32_e32 v188, 0, v188, vcc
	v_cndmask_b32_e32 v189, 0, v189, vcc
	v_cndmask_b32_e32 v190, 0, v190, vcc
	v_cndmask_b32_e32 v191, 0, v191, vcc
	v_cndmask_b32_e32 v192, 0, v192, vcc
	v_cndmask_b32_e32 v193, 0, v193, vcc
	v_cndmask_b32_e32 v194, 0, v194, vcc
	v_cndmask_b32_e32 v195, 0, v195, vcc
	v_cndmask_b32_e32 v196, 0, v196, vcc
	v_cndmask_b32_e32 v197, 0, v197, vcc
	v_cndmask_b32_e32 v198, 0, v198, vcc
	v_cndmask_b32_e32 v199, 0, v199, vcc
	ds_write2_b32 v24, v184, v185 offset1:1
	ds_write2_b32 v24, v186, v187 offset0:2 offset1:3
	ds_write2_b32 v25, v188, v189 offset1:1
	ds_write2_b32 v25, v190, v191 offset0:2 offset1:3
	ds_write2_b32 v26, v192, v193 offset1:1
	ds_write2_b32 v26, v194, v195 offset0:2 offset1:3
	ds_write2_b32 v27, v196, v197 offset1:1
	ds_write2_b32 v27, v198, v199 offset0:2 offset1:3
	s_waitcnt lgkmcnt(0)
	s_barrier
	v_add_u32_e32 v40, s27, v37
	v_add_u32_e32 v40, 448, v40
	v_min_u32_e32 v40, s52, v40
	v_lshl_add_u32 v224, v40, 2, v38
	v_add_u32_e32 v225, s51, v224
	v_add_u32_e32 v226, s51, v225
	v_add_u32_e32 v227, s51, v226
	global_load_dwordx4 v[184:187], v224, s[24:25] nt
	global_load_dwordx4 v[188:191], v225, s[24:25] nt
	global_load_dwordx4 v[192:195], v226, s[24:25] nt
	global_load_dwordx4 v[196:199], v227, s[24:25] nt
	ds_read2_b32 v[200:201], v32 offset0:0 offset1:65
	ds_read2_b32 v[202:203], v32 offset0:130 offset1:195
	ds_read2_b32 v[204:205], v33 offset0:4 offset1:69
	ds_read2_b32 v[206:207], v33 offset0:134 offset1:199
	ds_read2_b32 v[208:209], v34 offset0:8 offset1:73
	ds_read2_b32 v[210:211], v34 offset0:138 offset1:203
	ds_read2_b32 v[212:213], v35 offset0:12 offset1:77
	ds_read2_b32 v[214:215], v35 offset0:142 offset1:207
	s_waitcnt lgkmcnt(0)
	v_cvt_pk_bf16_f32 v216, v200, v201
	v_cvt_pk_bf16_f32 v217, v202, v203
	v_cvt_pk_bf16_f32 v218, v204, v205
	v_cvt_pk_bf16_f32 v219, v206, v207
	v_cvt_pk_bf16_f32 v220, v208, v209
	v_cvt_pk_bf16_f32 v221, v210, v211
	v_cvt_pk_bf16_f32 v222, v212, v213
	v_cvt_pk_bf16_f32 v223, v214, v215
	global_store_dwordx4 v39, v[216:219], s[20:21]
	global_store_dwordx4 v39, v[220:223], s[20:21] offset:16
	v_add_u32_e32 v39, s53, v39
	s_waitcnt vmcnt(8)
	v_add_u32_e32 v40, s27, v37
	v_add_u32_e32 v40, 384, v40
	v_cmp_gt_u32_e32 vcc, s0, v40
	s_nop 1
	v_cndmask_b32_e32 v168, 0, v168, vcc
	v_cndmask_b32_e32 v169, 0, v169, vcc
	v_cndmask_b32_e32 v170, 0, v170, vcc
	v_cndmask_b32_e32 v171, 0, v171, vcc
	v_cndmask_b32_e32 v172, 0, v172, vcc
	v_cndmask_b32_e32 v173, 0, v173, vcc
	v_cndmask_b32_e32 v174, 0, v174, vcc
	v_cndmask_b32_e32 v175, 0, v175, vcc
	v_cndmask_b32_e32 v176, 0, v176, vcc
	v_cndmask_b32_e32 v177, 0, v177, vcc
	v_cndmask_b32_e32 v178, 0, v178, vcc
	v_cndmask_b32_e32 v179, 0, v179, vcc
	v_cndmask_b32_e32 v180, 0, v180, vcc
	v_cndmask_b32_e32 v181, 0, v181, vcc
	v_cndmask_b32_e32 v182, 0, v182, vcc
	v_cndmask_b32_e32 v183, 0, v183, vcc
	ds_write2_b32 v20, v168, v169 offset1:1
	ds_write2_b32 v20, v170, v171 offset0:2 offset1:3
	ds_write2_b32 v21, v172, v173 offset1:1
	ds_write2_b32 v21, v174, v175 offset0:2 offset1:3
	ds_write2_b32 v22, v176, v177 offset1:1
	ds_write2_b32 v22, v178, v179 offset0:2 offset1:3
	ds_write2_b32 v23, v180, v181 offset1:1
	ds_write2_b32 v23, v182, v183 offset0:2 offset1:3
	s_waitcnt lgkmcnt(0)
	s_barrier
	ds_read2_b32 v[200:201], v28 offset0:0 offset1:65
	ds_read2_b32 v[202:203], v28 offset0:130 offset1:195
	ds_read2_b32 v[204:205], v29 offset0:4 offset1:69
	ds_read2_b32 v[206:207], v29 offset0:134 offset1:199
	ds_read2_b32 v[208:209], v30 offset0:8 offset1:73
	ds_read2_b32 v[210:211], v30 offset0:138 offset1:203
	ds_read2_b32 v[212:213], v31 offset0:12 offset1:77
	ds_read2_b32 v[214:215], v31 offset0:142 offset1:207
	s_waitcnt lgkmcnt(0)
	v_cvt_pk_bf16_f32 v216, v200, v201
	v_cvt_pk_bf16_f32 v217, v202, v203
	v_cvt_pk_bf16_f32 v218, v204, v205
	v_cvt_pk_bf16_f32 v219, v206, v207
	v_cvt_pk_bf16_f32 v220, v208, v209
	v_cvt_pk_bf16_f32 v221, v210, v211
	v_cvt_pk_bf16_f32 v222, v212, v213
	v_cvt_pk_bf16_f32 v223, v214, v215
	global_store_dwordx4 v39, v[216:219], s[20:21]
	global_store_dwordx4 v39, v[220:223], s[20:21] offset:16
	v_add_u32_e32 v39, s53, v39
	s_waitcnt vmcnt(4)
	v_add_u32_e32 v40, s27, v37
	v_add_u32_e32 v40, 448, v40
	v_cmp_gt_u32_e32 vcc, s0, v40
	s_nop 1
	v_cndmask_b32_e32 v184, 0, v184, vcc
	v_cndmask_b32_e32 v185, 0, v185, vcc
	v_cndmask_b32_e32 v186, 0, v186, vcc
	v_cndmask_b32_e32 v187, 0, v187, vcc
	v_cndmask_b32_e32 v188, 0, v188, vcc
	v_cndmask_b32_e32 v189, 0, v189, vcc
	v_cndmask_b32_e32 v190, 0, v190, vcc
	v_cndmask_b32_e32 v191, 0, v191, vcc
	v_cndmask_b32_e32 v192, 0, v192, vcc
	v_cndmask_b32_e32 v193, 0, v193, vcc
	v_cndmask_b32_e32 v194, 0, v194, vcc
	v_cndmask_b32_e32 v195, 0, v195, vcc
	v_cndmask_b32_e32 v196, 0, v196, vcc
	v_cndmask_b32_e32 v197, 0, v197, vcc
	v_cndmask_b32_e32 v198, 0, v198, vcc
	v_cndmask_b32_e32 v199, 0, v199, vcc
	ds_write2_b32 v24, v184, v185 offset1:1
	ds_write2_b32 v24, v186, v187 offset0:2 offset1:3
	ds_write2_b32 v25, v188, v189 offset1:1
	ds_write2_b32 v25, v190, v191 offset0:2 offset1:3
	ds_write2_b32 v26, v192, v193 offset1:1
	ds_write2_b32 v26, v194, v195 offset0:2 offset1:3
	ds_write2_b32 v27, v196, v197 offset1:1
	ds_write2_b32 v27, v198, v199 offset0:2 offset1:3
	s_waitcnt lgkmcnt(0)
	s_barrier
	ds_read2_b32 v[200:201], v32 offset0:0 offset1:65
	ds_read2_b32 v[202:203], v32 offset0:130 offset1:195
	ds_read2_b32 v[204:205], v33 offset0:4 offset1:69
	ds_read2_b32 v[206:207], v33 offset0:134 offset1:199
	ds_read2_b32 v[208:209], v34 offset0:8 offset1:73
	ds_read2_b32 v[210:211], v34 offset0:138 offset1:203
	ds_read2_b32 v[212:213], v35 offset0:12 offset1:77
	ds_read2_b32 v[214:215], v35 offset0:142 offset1:207
	s_waitcnt lgkmcnt(0)
	v_cvt_pk_bf16_f32 v216, v200, v201
	v_cvt_pk_bf16_f32 v217, v202, v203
	v_cvt_pk_bf16_f32 v218, v204, v205
	v_cvt_pk_bf16_f32 v219, v206, v207
	v_cvt_pk_bf16_f32 v220, v208, v209
	v_cvt_pk_bf16_f32 v221, v210, v211
	v_cvt_pk_bf16_f32 v222, v212, v213
	v_cvt_pk_bf16_f32 v223, v214, v215
	global_store_dwordx4 v39, v[216:219], s[20:21]
	global_store_dwordx4 v39, v[220:223], s[20:21] offset:16
	s_waitcnt lgkmcnt(0)
	s_barrier
	s_mov_b64 s[20:21], 0
	s_branch .LBB0_54

.LBB0_608:
	s_or_b64 exec, exec, s[20:21]
	s_waitcnt lgkmcnt(0)
	s_barrier
	ds_read_b32 v0, v117 offset:53264
	v_readlane_b32 s2, v162, 25
	s_mov_b64 s[20:21], -1
	s_waitcnt lgkmcnt(0)
	v_readfirstlane_b32 s35, v0
	v_cmp_le_i32_e32 vcc, s2, v0
	s_cbranch_vccnz .LBB0_603
	s_cmp_gt_i32 s35, 63
	s_cbranch_scc0 .LBB0_739
	s_cmpk_gt_u32 s35, 0x23f
	s_cbranch_scc0 .LBB0_723
	s_cmpk_gt_u32 s35, 0x33f
	s_cbranch_scc0 .LBB0_644
	s_cmpk_gt_u32 s35, 0x73f
	s_cbranch_scc0 .LBB0_639
	s_cmpk_gt_u32 s35, 0x87f
	s_cbranch_scc0 .LBB0_634
	s_sub_u32 s35, s35, 2176
	s_lshl_b32 s35, s35, 3
	s_add_u32 s35, s35, 2176
	s_add_i32 s2, s35, 0xfffff780
	s_cmpk_lt_u32 s2, 0x18c0
	s_movk_i32 s3, 0x840
	s_cselect_b32 s3, s3, 0xb40
	s_cmpk_gt_u32 s2, 0x107f
	s_cselect_b32 s40, s3, 0x580
	s_add_i32 s40, s40, s2
	s_cmpk_gt_u32 s40, 0x15ff
	s_mov_b64 s[38:39], -1
	s_cbranch_scc0 .LBB0_623
	s_cmpk_gt_u32 s40, 0x20ff
	s_mov_b64 s[22:23], -1
	s_cbranch_scc0 .LBB0_620
	s_cmpk_gt_u32 s40, 0x26ff
	s_cbranch_scc0 .LBB0_618
	v_readlane_b32 s4, v164, 17
	s_add_i32 s2, s40, 0xffffd900
	v_readlane_b32 s8, v164, 21
	v_readlane_b32 s9, v164, 22
	v_readlane_b32 s10, v164, 23
	v_readlane_b32 s11, v164, 24
	v_readlane_b32 s12, v164, 25
	v_readlane_b32 s13, v164, 26
	v_readlane_b32 s14, v164, 27
	v_readlane_b32 s15, v164, 28
	s_lshr_b32 s36, s2, 8
	v_readlane_b32 s16, v164, 29
	v_readlane_b32 s17, v164, 30
	v_readlane_b32 s18, v164, 31
	v_readlane_b32 s19, v164, 32
	s_mov_b64 s[8:9], s[12:13]
	s_and_b32 s3, s40, 0xff
	s_lshl_b64 s[20:21], s[36:37], 22
	s_mov_b64 s[10:11], s[14:15]
	s_mov_b64 s[12:13], s[16:17]
	v_readlane_b32 s5, v164, 18
	v_readlane_b32 s6, v164, 19
	v_readlane_b32 s7, v164, 20
	s_mov_b64 s[14:15], s[18:19]
	s_add_u32 s24, s12, s20
	s_addc_u32 s25, s13, s21
	v_readlane_b32 s4, v163, 1
	s_lshl_b64 s[20:21], s[36:37], 21
	v_readlane_b32 s14, v163, 11
	v_readlane_b32 s15, v163, 12
	s_add_u32 s20, s14, s20
	v_readlane_b32 s5, v163, 2
	v_readlane_b32 s6, v163, 3
	v_readlane_b32 s7, v163, 4
	v_readlane_b32 s8, v163, 5
	v_readlane_b32 s9, v163, 6
	v_readlane_b32 s10, v163, 7
	v_readlane_b32 s11, v163, 8
	v_readlane_b32 s12, v163, 9
	v_readlane_b32 s13, v163, 10
	v_readlane_b32 s16, v163, 13
	v_readlane_b32 s17, v163, 14
	v_readlane_b32 s18, v163, 15
	v_readlane_b32 s19, v163, 16
	s_addc_u32 s21, s15, s21
	s_mov_b64 s[22:23], 0

.LBB0_625:
	s_and_b32 s38, 0xffff, s36
	v_cvt_f32_u32_e32 v0, s38
	s_and_b32 s38, s3, 0xffff
	v_cvt_f32_u32_e32 v1, s38
	s_waitcnt vmcnt(5)
	v_mov_b32_e32 v8, v128
	v_rcp_iflag_f32_e32 v2, v0
	v_mov_b32_e32 v4, 0
	v_ashrrev_i32_e32 v9, 4, v8
	v_mul_f32_e32 v2, v1, v2
	v_trunc_f32_e32 v2, v2
	v_cvt_u32_f32_e32 v3, v2
	v_fma_f32 v1, -v2, v0, v1
	v_cmp_ge_f32_e64 s[38:39], |v1|, v0
	s_cmp_lg_u64 s[38:39], 0
	v_readfirstlane_b32 s38, v3
	s_addc_u32 s38, s38, 0
	s_and_b32 s39, s38, 0xffff
	s_mul_i32 s38, s38, s36
	s_sub_i32 s3, s3, s38
	s_lshl_b32 s3, s3, 6
	v_lshlrev_b32_e32 v0, 2, v8
	s_and_b32 s3, s3, 0xffc0
	v_and_b32_e32 v1, 60, v0
	v_or_b32_e32 v0, s3, v1
	v_lshlrev_b32_e32 v116, 2, v0
	s_lshl_b32 s36, s39, 6
	v_cmp_gt_u32_e32 vcc, s2, v0
	v_lshl_add_u64 v[6:7], s[24:25], 0, v[116:117]
	v_lshrrev_b32_e32 v36, 4, v128
	v_and_b32_e32 v37, 15, v128
	v_lshlrev_b32_e32 v37, 2, v37
	s_movk_i32 s50, 0x104
	v_mul_lo_u32 v41, v36, s50
	v_lshl_add_u32 v20, v37, 2, v41
	v_add_u32_e32 v21, 0x1040, v20
	v_add_u32_e32 v22, 0x2080, v20
	v_add_u32_e32 v23, 0x30c0, v20
	v_add_u32_e32 v24, 0x4200, v20
	v_add_u32_e32 v25, 0x4200, v21
	v_add_u32_e32 v26, 0x4200, v22
	v_add_u32_e32 v27, 0x4200, v23
	v_and_b32_e32 v41, 3, v128
	v_lshlrev_b32_e32 v41, 4, v41
	v_mul_lo_u32 v28, v41, s50
	v_and_b32_e32 v42, -4, v128
	v_add_u32_e32 v28, v28, v42
	v_add_u32_e32 v29, 0x400, v28
	v_add_u32_e32 v30, 0x800, v28
	v_add_u32_e32 v31, 0xc00, v28
	v_add_u32_e32 v32, 0x4200, v28
	v_add_u32_e32 v33, 0x4200, v29
	v_add_u32_e32 v34, 0x4200, v30
	v_add_u32_e32 v35, 0x4200, v31
	v_add_u32_e32 v38, s36, v36
	v_mul_lo_u32 v38, v38, s2
	v_lshlrev_b32_e32 v38, 2, v38
	s_lshl_b32 s51, s2, 6
	s_sub_u32 s52, s2, 4
	v_lshrrev_b32_e32 v39, 2, v128
	v_add_u32_e32 v39, s3, v39
	v_mul_lo_u32 v39, v39, s22
	v_add_u32_e32 v39, s36, v39
	v_add_u32_e32 v39, v41, v39
	v_lshlrev_b32_e32 v39, 1, v39
	s_lshl_b32 s53, s22, 7
	v_add_u32_e32 v40, s3, v37
	v_min_u32_e32 v40, s52, v40
	v_lshl_add_u32 v224, v40, 2, v38
	v_add_u32_e32 v225, s51, v224
	v_add_u32_e32 v226, s51, v225
	v_add_u32_e32 v227, s51, v226
	global_load_dwordx4 v[168:171], v224, s[24:25] nt
	global_load_dwordx4 v[172:175], v225, s[24:25] nt
	global_load_dwordx4 v[176:179], v226, s[24:25] nt
	global_load_dwordx4 v[180:183], v227, s[24:25] nt
	v_add_u32_e32 v40, s3, v37
	v_add_u32_e32 v40, 64, v40
	v_min_u32_e32 v40, s52, v40
	v_lshl_add_u32 v224, v40, 2, v38
	v_add_u32_e32 v225, s51, v224
	v_add_u32_e32 v226, s51, v225
	v_add_u32_e32 v227, s51, v226
	global_load_dwordx4 v[184:187], v224, s[24:25] nt
	global_load_dwordx4 v[188:191], v225, s[24:25] nt
	global_load_dwordx4 v[192:195], v226, s[24:25] nt
	global_load_dwordx4 v[196:199], v227, s[24:25] nt
	s_waitcnt vmcnt(4)
	v_add_u32_e32 v40, s3, v37
	v_cmp_gt_u32_e32 vcc, s2, v40
	s_nop 1
	v_cndmask_b32_e32 v168, 0, v168, vcc
	v_cndmask_b32_e32 v169, 0, v169, vcc
	v_cndmask_b32_e32 v170, 0, v170, vcc
	v_cndmask_b32_e32 v171, 0, v171, vcc
	v_cndmask_b32_e32 v172, 0, v172, vcc
	v_cndmask_b32_e32 v173, 0, v173, vcc
	v_cndmask_b32_e32 v174, 0, v174, vcc
	v_cndmask_b32_e32 v175, 0, v175, vcc
	v_cndmask_b32_e32 v176, 0, v176, vcc
	v_cndmask_b32_e32 v177, 0, v177, vcc
	v_cndmask_b32_e32 v178, 0, v178, vcc
	v_cndmask_b32_e32 v179, 0, v179, vcc
	v_cndmask_b32_e32 v180, 0, v180, vcc
	v_cndmask_b32_e32 v181, 0, v181, vcc
	v_cndmask_b32_e32 v182, 0, v182, vcc
	v_cndmask_b32_e32 v183, 0, v183, vcc
	ds_write2_b32 v20, v168, v169 offset1:1
	ds_write2_b32 v20, v170, v171 offset0:2 offset1:3
	ds_write2_b32 v21, v172, v173 offset1:1
	ds_write2_b32 v21, v174, v175 offset0:2 offset1:3
	ds_write2_b32 v22, v176, v177 offset1:1
	ds_write2_b32 v22, v178, v179 offset0:2 offset1:3
	ds_write2_b32 v23, v180, v181 offset1:1
	ds_write2_b32 v23, v182, v183 offset0:2 offset1:3
	s_waitcnt lgkmcnt(0)
	s_barrier
	v_add_u32_e32 v40, s3, v37
	v_add_u32_e32 v40, 128, v40
	v_min_u32_e32 v40, s52, v40
	v_lshl_add_u32 v224, v40, 2, v38
	v_add_u32_e32 v225, s51, v224
	v_add_u32_e32 v226, s51, v225
	v_add_u32_e32 v227, s51, v226
	global_load_dwordx4 v[168:171], v224, s[24:25] nt
	global_load_dwordx4 v[172:175], v225, s[24:25] nt
	global_load_dwordx4 v[176:179], v226, s[24:25] nt
	global_load_dwordx4 v[180:183], v227, s[24:25] nt
	ds_read2_b32 v[200:201], v28 offset0:0 offset1:65
	ds_read2_b32 v[202:203], v28 offset0:130 offset1:195
	ds_read2_b32 v[204:205], v29 offset0:4 offset1:69
	ds_read2_b32 v[206:207], v29 offset0:134 offset1:199
	ds_read2_b32 v[208:209], v30 offset0:8 offset1:73
	ds_read2_b32 v[210:211], v30 offset0:138 offset1:203
	ds_read2_b32 v[212:213], v31 offset0:12 offset1:77
	ds_read2_b32 v[214:215], v31 offset0:142 offset1:207
	s_waitcnt lgkmcnt(0)
	v_cvt_pk_bf16_f32 v216, v200, v201
	v_cvt_pk_bf16_f32 v217, v202, v203
	v_cvt_pk_bf16_f32 v218, v204, v205
	v_cvt_pk_bf16_f32 v219, v206, v207
	v_cvt_pk_bf16_f32 v220, v208, v209
	v_cvt_pk_bf16_f32 v221, v210, v211
	v_cvt_pk_bf16_f32 v222, v212, v213
	v_cvt_pk_bf16_f32 v223, v214, v215
	global_store_dwordx4 v39, v[216:219], s[20:21]
	global_store_dwordx4 v39, v[220:223], s[20:21] offset:16
	v_add_u32_e32 v39, s53, v39
	s_waitcnt vmcnt(6)
	v_add_u32_e32 v40, s3, v37
	v_add_u32_e32 v40, 64, v40
	v_cmp_gt_u32_e32 vcc, s2, v40
	s_nop 1
	v_cndmask_b32_e32 v184, 0, v184, vcc
	v_cndmask_b32_e32 v185, 0, v185, vcc
	v_cndmask_b32_e32 v186, 0, v186, vcc
	v_cndmask_b32_e32 v187, 0, v187, vcc
	v_cndmask_b32_e32 v188, 0, v188, vcc
	v_cndmask_b32_e32 v189, 0, v189, vcc
	v_cndmask_b32_e32 v190, 0, v190, vcc
	v_cndmask_b32_e32 v191, 0, v191, vcc
	v_cndmask_b32_e32 v192, 0, v192, vcc
	v_cndmask_b32_e32 v193, 0, v193, vcc
	v_cndmask_b32_e32 v194, 0, v194, vcc
	v_cndmask_b32_e32 v195, 0, v195, vcc
	v_cndmask_b32_e32 v196, 0, v196, vcc
	v_cndmask_b32_e32 v197, 0, v197, vcc
	v_cndmask_b32_e32 v198, 0, v198, vcc
	v_cndmask_b32_e32 v199, 0, v199, vcc
	ds_write2_b32 v24, v184, v185 offset1:1
	ds_write2_b32 v24, v186, v187 offset0:2 offset1:3
	ds_write2_b32 v25, v188, v189 offset1:1
	ds_write2_b32 v25, v190, v191 offset0:2 offset1:3
	ds_write2_b32 v26, v192, v193 offset1:1
	ds_write2_b32 v26, v194, v195 offset0:2 offset1:3
	ds_write2_b32 v27, v196, v197 offset1:1
	ds_write2_b32 v27, v198, v199 offset0:2 offset1:3
	s_waitcnt lgkmcnt(0)
	s_barrier
	v_add_u32_e32 v40, s3, v37
	v_add_u32_e32 v40, 192, v40
	v_min_u32_e32 v40, s52, v40
	v_lshl_add_u32 v224, v40, 2, v38
	v_add_u32_e32 v225, s51, v224
	v_add_u32_e32 v226, s51, v225
	v_add_u32_e32 v227, s51, v226
	global_load_dwordx4 v[184:187], v224, s[24:25] nt
	global_load_dwordx4 v[188:191], v225, s[24:25] nt
	global_load_dwordx4 v[192:195], v226, s[24:25] nt
	global_load_dwordx4 v[196:199], v227, s[24:25] nt
	ds_read2_b32 v[200:201], v32 offset0:0 offset1:65
	ds_read2_b32 v[202:203], v32 offset0:130 offset1:195
	ds_read2_b32 v[204:205], v33 offset0:4 offset1:69
	ds_read2_b32 v[206:207], v33 offset0:134 offset1:199
	ds_read2_b32 v[208:209], v34 offset0:8 offset1:73
	ds_read2_b32 v[210:211], v34 offset0:138 offset1:203
	ds_read2_b32 v[212:213], v35 offset0:12 offset1:77
	ds_read2_b32 v[214:215], v35 offset0:142 offset1:207
	s_waitcnt lgkmcnt(0)
	v_cvt_pk_bf16_f32 v216, v200, v201
	v_cvt_pk_bf16_f32 v217, v202, v203
	v_cvt_pk_bf16_f32 v218, v204, v205
	v_cvt_pk_bf16_f32 v219, v206, v207
	v_cvt_pk_bf16_f32 v220, v208, v209
	v_cvt_pk_bf16_f32 v221, v210, v211
	v_cvt_pk_bf16_f32 v222, v212, v213
	v_cvt_pk_bf16_f32 v223, v214, v215
	global_store_dwordx4 v39, v[216:219], s[20:21]
	global_store_dwordx4 v39, v[220:223], s[20:21] offset:16
	v_add_u32_e32 v39, s53, v39
	s_waitcnt vmcnt(8)
	v_add_u32_e32 v40, s3, v37
	v_add_u32_e32 v40, 128, v40
	v_cmp_gt_u32_e32 vcc, s2, v40
	s_nop 1
	v_cndmask_b32_e32 v168, 0, v168, vcc
	v_cndmask_b32_e32 v169, 0, v169, vcc
	v_cndmask_b32_e32 v170, 0, v170, vcc
	v_cndmask_b32_e32 v171, 0, v171, vcc
	v_cndmask_b32_e32 v172, 0, v172, vcc
	v_cndmask_b32_e32 v173, 0, v173, vcc
	v_cndmask_b32_e32 v174, 0, v174, vcc
	v_cndmask_b32_e32 v175, 0, v175, vcc
	v_cndmask_b32_e32 v176, 0, v176, vcc
	v_cndmask_b32_e32 v177, 0, v177, vcc
	v_cndmask_b32_e32 v178, 0, v178, vcc
	v_cndmask_b32_e32 v179, 0, v179, vcc
	v_cndmask_b32_e32 v180, 0, v180, vcc
	v_cndmask_b32_e32 v181, 0, v181, vcc
	v_cndmask_b32_e32 v182, 0, v182, vcc
	v_cndmask_b32_e32 v183, 0, v183, vcc
	ds_write2_b32 v20, v168, v169 offset1:1
	ds_write2_b32 v20, v170, v171 offset0:2 offset1:3
	ds_write2_b32 v21, v172, v173 offset1:1
	ds_write2_b32 v21, v174, v175 offset0:2 offset1:3
	ds_write2_b32 v22, v176, v177 offset1:1
	ds_write2_b32 v22, v178, v179 offset0:2 offset1:3
	ds_write2_b32 v23, v180, v181 offset1:1
	ds_write2_b32 v23, v182, v183 offset0:2 offset1:3
	s_waitcnt lgkmcnt(0)
	s_barrier
	v_add_u32_e32 v40, s3, v37
	v_add_u32_e32 v40, 256, v40
	v_min_u32_e32 v40, s52, v40
	v_lshl_add_u32 v224, v40, 2, v38
	v_add_u32_e32 v225, s51, v224
	v_add_u32_e32 v226, s51, v225
	v_add_u32_e32 v227, s51, v226
	global_load_dwordx4 v[168:171], v224, s[24:25] nt
	global_load_dwordx4 v[172:175], v225, s[24:25] nt
	global_load_dwordx4 v[176:179], v226, s[24:25] nt
	global_load_dwordx4 v[180:183], v227, s[24:25] nt
	ds_read2_b32 v[200:201], v28 offset0:0 offset1:65
	ds_read2_b32 v[202:203], v28 offset0:130 offset1:195
	ds_read2_b32 v[204:205], v29 offset0:4 offset1:69
	ds_read2_b32 v[206:207], v29 offset0:134 offset1:199
	ds_read2_b32 v[208:209], v30 offset0:8 offset1:73
	ds_read2_b32 v[210:211], v30 offset0:138 offset1:203
	ds_read2_b32 v[212:213], v31 offset0:12 offset1:77
	ds_read2_b32 v[214:215], v31 offset0:142 offset1:207
	s_waitcnt lgkmcnt(0)
	v_cvt_pk_bf16_f32 v216, v200, v201
	v_cvt_pk_bf16_f32 v217, v202, v203
	v_cvt_pk_bf16_f32 v218, v204, v205
	v_cvt_pk_bf16_f32 v219, v206, v207
	v_cvt_pk_bf16_f32 v220, v208, v209
	v_cvt_pk_bf16_f32 v221, v210, v211
	v_cvt_pk_bf16_f32 v222, v212, v213
	v_cvt_pk_bf16_f32 v223, v214, v215
	global_store_dwordx4 v39, v[216:219], s[20:21]
	global_store_dwordx4 v39, v[220:223], s[20:21] offset:16
	v_add_u32_e32 v39, s53, v39
	s_waitcnt vmcnt(8)
	v_add_u32_e32 v40, s3, v37
	v_add_u32_e32 v40, 192, v40
	v_cmp_gt_u32_e32 vcc, s2, v40
	s_nop 1
	v_cndmask_b32_e32 v184, 0, v184, vcc
	v_cndmask_b32_e32 v185, 0, v185, vcc
	v_cndmask_b32_e32 v186, 0, v186, vcc
	v_cndmask_b32_e32 v187, 0, v187, vcc
	v_cndmask_b32_e32 v188, 0, v188, vcc
	v_cndmask_b32_e32 v189, 0, v189, vcc
	v_cndmask_b32_e32 v190, 0, v190, vcc
	v_cndmask_b32_e32 v191, 0, v191, vcc
	v_cndmask_b32_e32 v192, 0, v192, vcc
	v_cndmask_b32_e32 v193, 0, v193, vcc
	v_cndmask_b32_e32 v194, 0, v194, vcc
	v_cndmask_b32_e32 v195, 0, v195, vcc
	v_cndmask_b32_e32 v196, 0, v196, vcc
	v_cndmask_b32_e32 v197, 0, v197, vcc
	v_cndmask_b32_e32 v198, 0, v198, vcc
	v_cndmask_b32_e32 v199, 0, v199, vcc
	ds_write2_b32 v24, v184, v185 offset1:1
	ds_write2_b32 v24, v186, v187 offset0:2 offset1:3
	ds_write2_b32 v25, v188, v189 offset1:1
	ds_write2_b32 v25, v190, v191 offset0:2 offset1:3
	ds_write2_b32 v26, v192, v193 offset1:1
	ds_write2_b32 v26, v194, v195 offset0:2 offset1:3
	ds_write2_b32 v27, v196, v197 offset1:1
	ds_write2_b32 v27, v198, v199 offset0:2 offset1:3
	s_waitcnt lgkmcnt(0)
	s_barrier
	v_add_u32_e32 v40, s3, v37
	v_add_u32_e32 v40, 320, v40
	v_min_u32_e32 v40, s52, v40
	v_lshl_add_u32 v224, v40, 2, v38
	v_add_u32_e32 v225, s51, v224
	v_add_u32_e32 v226, s51, v225
	v_add_u32_e32 v227, s51, v226
	global_load_dwordx4 v[184:187], v224, s[24:25] nt
	global_load_dwordx4 v[188:191], v225, s[24:25] nt
	global_load_dwordx4 v[192:195], v226, s[24:25] nt
	global_load_dwordx4 v[196:199], v227, s[24:25] nt
	ds_read2_b32 v[200:201], v32 offset0:0 offset1:65
	ds_read2_b32 v[202:203], v32 offset0:130 offset1:195
	ds_read2_b32 v[204:205], v33 offset0:4 offset1:69
	ds_read2_b32 v[206:207], v33 offset0:134 offset1:199
	ds_read2_b32 v[208:209], v34 offset0:8 offset1:73
	ds_read2_b32 v[210:211], v34 offset0:138 offset1:203
	ds_read2_b32 v[212:213], v35 offset0:12 offset1:77
	ds_read2_b32 v[214:215], v35 offset0:142 offset1:207
	s_waitcnt lgkmcnt(0)
	v_cvt_pk_bf16_f32 v216, v200, v201
	v_cvt_pk_bf16_f32 v217, v202, v203
	v_cvt_pk_bf16_f32 v218, v204, v205
	v_cvt_pk_bf16_f32 v219, v206, v207
	v_cvt_pk_bf16_f32 v220, v208, v209
	v_cvt_pk_bf16_f32 v221, v210, v211
	v_cvt_pk_bf16_f32 v222, v212, v213
	v_cvt_pk_bf16_f32 v223, v214, v215
	global_store_dwordx4 v39, v[216:219], s[20:21]
	global_store_dwordx4 v39, v[220:223], s[20:21] offset:16
	v_add_u32_e32 v39, s53, v39
	s_waitcnt vmcnt(8)
	v_add_u32_e32 v40, s3, v37
	v_add_u32_e32 v40, 256, v40
	v_cmp_gt_u32_e32 vcc, s2, v40
	s_nop 1
	v_cndmask_b32_e32 v168, 0, v168, vcc
	v_cndmask_b32_e32 v169, 0, v169, vcc
	v_cndmask_b32_e32 v170, 0, v170, vcc
	v_cndmask_b32_e32 v171, 0, v171, vcc
	v_cndmask_b32_e32 v172, 0, v172, vcc
	v_cndmask_b32_e32 v173, 0, v173, vcc
	v_cndmask_b32_e32 v174, 0, v174, vcc
	v_cndmask_b32_e32 v175, 0, v175, vcc
	v_cndmask_b32_e32 v176, 0, v176, vcc
	v_cndmask_b32_e32 v177, 0, v177, vcc
	v_cndmask_b32_e32 v178, 0, v178, vcc
	v_cndmask_b32_e32 v179, 0, v179, vcc
	v_cndmask_b32_e32 v180, 0, v180, vcc
	v_cndmask_b32_e32 v181, 0, v181, vcc
	v_cndmask_b32_e32 v182, 0, v182, vcc
	v_cndmask_b32_e32 v183, 0, v183, vcc
	ds_write2_b32 v20, v168, v169 offset1:1
	ds_write2_b32 v20, v170, v171 offset0:2 offset1:3
	ds_write2_b32 v21, v172, v173 offset1:1
	ds_write2_b32 v21, v174, v175 offset0:2 offset1:3
	ds_write2_b32 v22, v176, v177 offset1:1
	ds_write2_b32 v22, v178, v179 offset0:2 offset1:3
	ds_write2_b32 v23, v180, v181 offset1:1
	ds_write2_b32 v23, v182, v183 offset0:2 offset1:3
	s_waitcnt lgkmcnt(0)
	s_barrier
	v_add_u32_e32 v40, s3, v37
	v_add_u32_e32 v40, 384, v40
	v_min_u32_e32 v40, s52, v40
	v_lshl_add_u32 v224, v40, 2, v38
	v_add_u32_e32 v225, s51, v224
	v_add_u32_e32 v226, s51, v225
	v_add_u32_e32 v227, s51, v226
	global_load_dwordx4 v[168:171], v224, s[24:25] nt
	global_load_dwordx4 v[172:175], v225, s[24:25] nt
	global_load_dwordx4 v[176:179], v226, s[24:25] nt
	global_load_dwordx4 v[180:183], v227, s[24:25] nt
	ds_read2_b32 v[200:201], v28 offset0:0 offset1:65
	ds_read2_b32 v[202:203], v28 offset0:130 offset1:195
	ds_read2_b32 v[204:205], v29 offset0:4 offset1:69
	ds_read2_b32 v[206:207], v29 offset0:134 offset1:199
	ds_read2_b32 v[208:209], v30 offset0:8 offset1:73
	ds_read2_b32 v[210:211], v30 offset0:138 offset1:203
	ds_read2_b32 v[212:213], v31 offset0:12 offset1:77
	ds_read2_b32 v[214:215], v31 offset0:142 offset1:207
	s_waitcnt lgkmcnt(0)
	v_cvt_pk_bf16_f32 v216, v200, v201
	v_cvt_pk_bf16_f32 v217, v202, v203
	v_cvt_pk_bf16_f32 v218, v204, v205
	v_cvt_pk_bf16_f32 v219, v206, v207
	v_cvt_pk_bf16_f32 v220, v208, v209
	v_cvt_pk_bf16_f32 v221, v210, v211
	v_cvt_pk_bf16_f32 v222, v212, v213
	v_cvt_pk_bf16_f32 v223, v214, v215
	global_store_dwordx4 v39, v[216:219], s[20:21]
	global_store_dwordx4 v39, v[220:223], s[20:21] offset:16
	v_add_u32_e32 v39, s53, v39
	s_waitcnt vmcnt(8)
	v_add_u32_e32 v40, s3, v37
	v_add_u32_e32 v40, 320, v40
	v_cmp_gt_u32_e32 vcc, s2, v40
	s_nop 1
	v_cndmask_b32_e32 v184, 0, v184, vcc
	v_cndmask_b32_e32 v185, 0, v185, vcc
	v_cndmask_b32_e32 v186, 0, v186, vcc
	v_cndmask_b32_e32 v187, 0, v187, vcc
	v_cndmask_b32_e32 v188, 0, v188, vcc
	v_cndmask_b32_e32 v189, 0, v189, vcc
	v_cndmask_b32_e32 v190, 0, v190, vcc
	v_cndmask_b32_e32 v191, 0, v191, vcc
	v_cndmask_b32_e32 v192, 0, v192, vcc
	v_cndmask_b32_e32 v193, 0, v193, vcc
	v_cndmask_b32_e32 v194, 0, v194, vcc
	v_cndmask_b32_e32 v195, 0, v195, vcc
	v_cndmask_b32_e32 v196, 0, v196, vcc
	v_cndmask_b32_e32 v197, 0, v197, vcc
	v_cndmask_b32_e32 v198, 0, v198, vcc
	v_cndmask_b32_e32 v199, 0, v199, vcc
	ds_write2_b32 v24, v184, v185 offset1:1
	ds_write2_b32 v24, v186, v187 offset0:2 offset1:3
	ds_write2_b32 v25, v188, v189 offset1:1
	ds_write2_b32 v25, v190, v191 offset0:2 offset1:3
	ds_write2_b32 v26, v192, v193 offset1:1
	ds_write2_b32 v26, v194, v195 offset0:2 offset1:3
	ds_write2_b32 v27, v196, v197 offset1:1
	ds_write2_b32 v27, v198, v199 offset0:2 offset1:3
	s_waitcnt lgkmcnt(0)
	s_barrier
	v_add_u32_e32 v40, s3, v37
	v_add_u32_e32 v40, 448, v40
	v_min_u32_e32 v40, s52, v40
	v_lshl_add_u32 v224, v40, 2, v38
	v_add_u32_e32 v225, s51, v224
	v_add_u32_e32 v226, s51, v225
	v_add_u32_e32 v227, s51, v226
	global_load_dwordx4 v[184:187], v224, s[24:25] nt
	global_load_dwordx4 v[188:191], v225, s[24:25] nt
	global_load_dwordx4 v[192:195], v226, s[24:25] nt
	global_load_dwordx4 v[196:199], v227, s[24:25] nt
	ds_read2_b32 v[200:201], v32 offset0:0 offset1:65
	ds_read2_b32 v[202:203], v32 offset0:130 offset1:195
	ds_read2_b32 v[204:205], v33 offset0:4 offset1:69
	ds_read2_b32 v[206:207], v33 offset0:134 offset1:199
	ds_read2_b32 v[208:209], v34 offset0:8 offset1:73
	ds_read2_b32 v[210:211], v34 offset0:138 offset1:203
	ds_read2_b32 v[212:213], v35 offset0:12 offset1:77
	ds_read2_b32 v[214:215], v35 offset0:142 offset1:207
	s_waitcnt lgkmcnt(0)
	v_cvt_pk_bf16_f32 v216, v200, v201
	v_cvt_pk_bf16_f32 v217, v202, v203
	v_cvt_pk_bf16_f32 v218, v204, v205
	v_cvt_pk_bf16_f32 v219, v206, v207
	v_cvt_pk_bf16_f32 v220, v208, v209
	v_cvt_pk_bf16_f32 v221, v210, v211
	v_cvt_pk_bf16_f32 v222, v212, v213
	v_cvt_pk_bf16_f32 v223, v214, v215
	global_store_dwordx4 v39, v[216:219], s[20:21]
	global_store_dwordx4 v39, v[220:223], s[20:21] offset:16
	v_add_u32_e32 v39, s53, v39
	s_waitcnt vmcnt(8)
	v_add_u32_e32 v40, s3, v37
	v_add_u32_e32 v40, 384, v40
	v_cmp_gt_u32_e32 vcc, s2, v40
	s_nop 1
	v_cndmask_b32_e32 v168, 0, v168, vcc
	v_cndmask_b32_e32 v169, 0, v169, vcc
	v_cndmask_b32_e32 v170, 0, v170, vcc
	v_cndmask_b32_e32 v171, 0, v171, vcc
	v_cndmask_b32_e32 v172, 0, v172, vcc
	v_cndmask_b32_e32 v173, 0, v173, vcc
	v_cndmask_b32_e32 v174, 0, v174, vcc
	v_cndmask_b32_e32 v175, 0, v175, vcc
	v_cndmask_b32_e32 v176, 0, v176, vcc
	v_cndmask_b32_e32 v177, 0, v177, vcc
	v_cndmask_b32_e32 v178, 0, v178, vcc
	v_cndmask_b32_e32 v179, 0, v179, vcc
	v_cndmask_b32_e32 v180, 0, v180, vcc
	v_cndmask_b32_e32 v181, 0, v181, vcc
	v_cndmask_b32_e32 v182, 0, v182, vcc
	v_cndmask_b32_e32 v183, 0, v183, vcc
	ds_write2_b32 v20, v168, v169 offset1:1
	ds_write2_b32 v20, v170, v171 offset0:2 offset1:3
	ds_write2_b32 v21, v172, v173 offset1:1
	ds_write2_b32 v21, v174, v175 offset0:2 offset1:3
	ds_write2_b32 v22, v176, v177 offset1:1
	ds_write2_b32 v22, v178, v179 offset0:2 offset1:3
	ds_write2_b32 v23, v180, v181 offset1:1
	ds_write2_b32 v23, v182, v183 offset0:2 offset1:3
	s_waitcnt lgkmcnt(0)
	s_barrier
	ds_read2_b32 v[200:201], v28 offset0:0 offset1:65
	ds_read2_b32 v[202:203], v28 offset0:130 offset1:195
	ds_read2_b32 v[204:205], v29 offset0:4 offset1:69
	ds_read2_b32 v[206:207], v29 offset0:134 offset1:199
	ds_read2_b32 v[208:209], v30 offset0:8 offset1:73
	ds_read2_b32 v[210:211], v30 offset0:138 offset1:203
	ds_read2_b32 v[212:213], v31 offset0:12 offset1:77
	ds_read2_b32 v[214:215], v31 offset0:142 offset1:207
	s_waitcnt lgkmcnt(0)
	v_cvt_pk_bf16_f32 v216, v200, v201
	v_cvt_pk_bf16_f32 v217, v202, v203
	v_cvt_pk_bf16_f32 v218, v204, v205
	v_cvt_pk_bf16_f32 v219, v206, v207
	v_cvt_pk_bf16_f32 v220, v208, v209
	v_cvt_pk_bf16_f32 v221, v210, v211
	v_cvt_pk_bf16_f32 v222, v212, v213
	v_cvt_pk_bf16_f32 v223, v214, v215
	global_store_dwordx4 v39, v[216:219], s[20:21]
	global_store_dwordx4 v39, v[220:223], s[20:21] offset:16
	v_add_u32_e32 v39, s53, v39
	s_waitcnt vmcnt(4)
	v_add_u32_e32 v40, s3, v37
	v_add_u32_e32 v40, 448, v40
	v_cmp_gt_u32_e32 vcc, s2, v40
	s_nop 1
	v_cndmask_b32_e32 v184, 0, v184, vcc
	v_cndmask_b32_e32 v185, 0, v185, vcc
	v_cndmask_b32_e32 v186, 0, v186, vcc
	v_cndmask_b32_e32 v187, 0, v187, vcc
	v_cndmask_b32_e32 v188, 0, v188, vcc
	v_cndmask_b32_e32 v189, 0, v189, vcc
	v_cndmask_b32_e32 v190, 0, v190, vcc
	v_cndmask_b32_e32 v191, 0, v191, vcc
	v_cndmask_b32_e32 v192, 0, v192, vcc
	v_cndmask_b32_e32 v193, 0, v193, vcc
	v_cndmask_b32_e32 v194, 0, v194, vcc
	v_cndmask_b32_e32 v195, 0, v195, vcc
	v_cndmask_b32_e32 v196, 0, v196, vcc
	v_cndmask_b32_e32 v197, 0, v197, vcc
	v_cndmask_b32_e32 v198, 0, v198, vcc
	v_cndmask_b32_e32 v199, 0, v199, vcc
	ds_write2_b32 v24, v184, v185 offset1:1
	ds_write2_b32 v24, v186, v187 offset0:2 offset1:3
	ds_write2_b32 v25, v188, v189 offset1:1
	ds_write2_b32 v25, v190, v191 offset0:2 offset1:3
	ds_write2_b32 v26, v192, v193 offset1:1
	ds_write2_b32 v26, v194, v195 offset0:2 offset1:3
	ds_write2_b32 v27, v196, v197 offset1:1
	ds_write2_b32 v27, v198, v199 offset0:2 offset1:3
	s_waitcnt lgkmcnt(0)
	s_barrier
	ds_read2_b32 v[200:201], v32 offset0:0 offset1:65
	ds_read2_b32 v[202:203], v32 offset0:130 offset1:195
	ds_read2_b32 v[204:205], v33 offset0:4 offset1:69
	ds_read2_b32 v[206:207], v33 offset0:134 offset1:199
	ds_read2_b32 v[208:209], v34 offset0:8 offset1:73
	ds_read2_b32 v[210:211], v34 offset0:138 offset1:203
	ds_read2_b32 v[212:213], v35 offset0:12 offset1:77
	ds_read2_b32 v[214:215], v35 offset0:142 offset1:207
	s_waitcnt lgkmcnt(0)
	v_cvt_pk_bf16_f32 v216, v200, v201
	v_cvt_pk_bf16_f32 v217, v202, v203
	v_cvt_pk_bf16_f32 v218, v204, v205
	v_cvt_pk_bf16_f32 v219, v206, v207
	v_cvt_pk_bf16_f32 v220, v208, v209
	v_cvt_pk_bf16_f32 v221, v210, v211
	v_cvt_pk_bf16_f32 v222, v212, v213
	v_cvt_pk_bf16_f32 v223, v214, v215
	global_store_dwordx4 v39, v[216:219], s[20:21]
	global_store_dwordx4 v39, v[220:223], s[20:21] offset:16
	s_waitcnt lgkmcnt(0)
	s_barrier
	s_mov_b64 s[20:21], 0
	s_branch .LBB0_634
